# G4/G6 residual loads for first row-block issued before the last 16 MFMAs; G2 rope-table LDS fill overlapped with first K-tile staging
# speedup vs baseline: 1.0049x; 1.0049x over previous
.LBB0_224:
	s_or_b64 exec, exec, s[0:1]
	v_add_u32_e32 v222, v170, v168
	v_or_b32_e32 v223, v169, v167
	v_lshlrev_b32_e32 v221, 12, v222
	v_lshl_add_u32 v221, v223, 2, v221
	s_mov_b32 s0, s68
	s_mov_b32 s1, s69
	global_load_dword v189, v221, s[0:1]
	global_load_dword v205, v221, s[0:1] offset:128
	s_add_u32 s0, s68, 0x1000
	s_addc_u32 s1, s69, 0
	global_load_dword v190, v221, s[0:1]
	global_load_dword v206, v221, s[0:1] offset:128
	s_add_u32 s0, s68, 0x2000
	s_addc_u32 s1, s69, 0
	global_load_dword v191, v221, s[0:1]
	global_load_dword v207, v221, s[0:1] offset:128
	s_add_u32 s0, s68, 0x3000
	s_addc_u32 s1, s69, 0
	global_load_dword v192, v221, s[0:1]
	global_load_dword v208, v221, s[0:1] offset:128
	s_add_u32 s0, s68, 0x8000
	s_addc_u32 s1, s69, 0
	global_load_dword v193, v221, s[0:1]
	global_load_dword v209, v221, s[0:1] offset:128
	s_add_u32 s0, s68, 0x9000
	s_addc_u32 s1, s69, 0
	global_load_dword v194, v221, s[0:1]
	global_load_dword v210, v221, s[0:1] offset:128
	s_add_u32 s0, s68, 0xa000
	s_addc_u32 s1, s69, 0
	global_load_dword v195, v221, s[0:1]
	global_load_dword v211, v221, s[0:1] offset:128
	s_add_u32 s0, s68, 0xb000
	s_addc_u32 s1, s69, 0
	global_load_dword v196, v221, s[0:1]
	global_load_dword v212, v221, s[0:1] offset:128
	s_add_u32 s0, s68, 0x10000
	s_addc_u32 s1, s69, 0
	global_load_dword v197, v221, s[0:1]
	global_load_dword v213, v221, s[0:1] offset:128
	s_add_u32 s0, s68, 0x11000
	s_addc_u32 s1, s69, 0
	global_load_dword v198, v221, s[0:1]
	global_load_dword v214, v221, s[0:1] offset:128
	s_add_u32 s0, s68, 0x12000
	s_addc_u32 s1, s69, 0
	global_load_dword v199, v221, s[0:1]
	global_load_dword v215, v221, s[0:1] offset:128
	s_add_u32 s0, s68, 0x13000
	s_addc_u32 s1, s69, 0
	global_load_dword v200, v221, s[0:1]
	global_load_dword v216, v221, s[0:1] offset:128
	s_add_u32 s0, s68, 0x18000
	s_addc_u32 s1, s69, 0
	global_load_dword v201, v221, s[0:1]
	global_load_dword v217, v221, s[0:1] offset:128
	s_add_u32 s0, s68, 0x19000
	s_addc_u32 s1, s69, 0
	global_load_dword v202, v221, s[0:1]
	global_load_dword v218, v221, s[0:1] offset:128
	s_add_u32 s0, s68, 0x1a000
	s_addc_u32 s1, s69, 0
	global_load_dword v203, v221, s[0:1]
	global_load_dword v219, v221, s[0:1] offset:128
	s_add_u32 s0, s68, 0x1b000
	s_addc_u32 s1, s69, 0
	global_load_dword v204, v221, s[0:1]
	global_load_dword v220, v221, s[0:1] offset:128
	v_add_u32_e32 v131, v130, v172
	ds_read_b128 v[132:135], v131
	ds_read_b128 v[136:139], v131 offset:4096
	ds_read_b128 v[140:143], v131 offset:8192
	ds_read_b128 v[150:153], v131 offset:12288
	v_add_u32_e32 v131, v128, v172
	ds_read_b128 v[154:157], v131 offset:32768
	ds_read_b128 v[158:161], v131 offset:36864
	s_setprio 1
	s_waitcnt lgkmcnt(0)
	v_mfma_f32_32x32x16_bf16 v[112:127], v[132:135], v[154:157], v[112:127]
	v_mfma_f32_32x32x16_bf16 v[96:111], v[132:135], v[158:161], v[96:111]
	v_mfma_f32_32x32x16_bf16 v[80:95], v[136:139], v[154:157], v[80:95]
	v_mfma_f32_32x32x16_bf16 v[64:79], v[136:139], v[158:161], v[64:79]
	v_mfma_f32_32x32x16_bf16 v[48:63], v[140:143], v[154:157], v[48:63]
	v_mfma_f32_32x32x16_bf16 v[32:47], v[140:143], v[158:161], v[32:47]
	v_mfma_f32_32x32x16_bf16 v[16:31], v[150:153], v[154:157], v[16:31]
	v_mfma_f32_32x32x16_bf16 v[0:15], v[150:153], v[158:161], v[0:15]
	s_setprio 0
	v_add_u32_e32 v142, v130, v171
	ds_read_b128 v[130:133], v142
	ds_read_b128 v[134:137], v142 offset:4096
	ds_read_b128 v[138:141], v142 offset:8192
	ds_read_b128 v[142:145], v142 offset:12288
	v_add_u32_e32 v128, v128, v171
	ds_read_b128 v[150:153], v128 offset:32768
	ds_read_b128 v[154:157], v128 offset:36864
	s_setprio 1
	s_waitcnt lgkmcnt(0)
	v_mfma_f32_32x32x16_bf16 v[112:127], v[130:133], v[150:153], v[112:127]
	v_mfma_f32_32x32x16_bf16 v[96:111], v[130:133], v[154:157], v[96:111]
	v_mfma_f32_32x32x16_bf16 v[80:95], v[134:137], v[150:153], v[80:95]
	v_mfma_f32_32x32x16_bf16 v[64:79], v[134:137], v[154:157], v[64:79]
	v_mfma_f32_32x32x16_bf16 v[48:63], v[138:141], v[150:153], v[48:63]
	v_mfma_f32_32x32x16_bf16 v[32:47], v[138:141], v[154:157], v[32:47]
	v_mfma_f32_32x32x16_bf16 v[16:31], v[142:145], v[150:153], v[16:31]
	v_mfma_f32_32x32x16_bf16 v[0:15], v[142:145], v[154:157], v[0:15]
	s_setprio 0
	v_or_b32_e32 v144, v169, v167
	v_readlane_b32 s1, v254, 62
	s_movk_i32 s0, 0x1fff
	v_add_u32_e32 v128, 0xffffe000, v170
	v_cmp_lt_i32_e32 vcc, s0, v170
	v_lshrrev_b32_e32 v128, 10, v128
	v_add_u32_e32 v128, 1, v128
	v_cndmask_b32_e32 v128, 0, v128, vcc
	v_mov_b64_e32 v[130:131], s[66:67]
	v_add_u32_e32 v128, s1, v128
	s_movk_i32 s0, 0x6000
	v_mad_u64_u32 v[130:131], s[0:1], v128, s0, v[130:131]
	s_mov_b64 s[0:1], 0x5000
	v_lshl_add_u64 v[130:131], v[130:131], 0, s[0:1]
	v_mov_b32_e32 v135, 0
	v_lshlrev_b32_e32 v134, 2, v144
	v_lshl_add_u64 v[130:131], v[130:131], 0, v[134:135]
	global_load_dword v128, v[130:131], off
	global_load_dword v133, v[130:131], off offset:128
	s_add_u32 s0, s68, 0x20000
	s_addc_u32 s1, s69, 0
	global_load_dword v150, v221, s[0:1]
	global_load_dword v172, v221, s[0:1] offset:128
	s_add_u32 s0, s68, 0x21000
	s_addc_u32 s1, s69, 0
	global_load_dword v151, v221, s[0:1]
	global_load_dword v173, v221, s[0:1] offset:128
	s_add_u32 s0, s68, 0x22000
	s_addc_u32 s1, s69, 0
	global_load_dword v152, v221, s[0:1]
	global_load_dword v174, v221, s[0:1] offset:128
	s_add_u32 s0, s68, 0x23000
	s_addc_u32 s1, s69, 0
	global_load_dword v153, v221, s[0:1]
	global_load_dword v175, v221, s[0:1] offset:128
	s_add_u32 s0, s68, 0x28000
	s_addc_u32 s1, s69, 0
	global_load_dword v154, v221, s[0:1]
	global_load_dword v176, v221, s[0:1] offset:128
	s_add_u32 s0, s68, 0x29000
	s_addc_u32 s1, s69, 0
	global_load_dword v155, v221, s[0:1]
	global_load_dword v177, v221, s[0:1] offset:128
	s_add_u32 s0, s68, 0x2a000
	s_addc_u32 s1, s69, 0
	global_load_dword v156, v221, s[0:1]
	global_load_dword v178, v221, s[0:1] offset:128
	s_add_u32 s0, s68, 0x2b000
	s_addc_u32 s1, s69, 0
	global_load_dword v157, v221, s[0:1]
	global_load_dword v179, v221, s[0:1] offset:128
	s_add_u32 s0, s68, 0x30000
	s_addc_u32 s1, s69, 0
	global_load_dword v158, v221, s[0:1]
	global_load_dword v180, v221, s[0:1] offset:128
	s_add_u32 s0, s68, 0x31000
	s_addc_u32 s1, s69, 0
	global_load_dword v159, v221, s[0:1]
	global_load_dword v181, v221, s[0:1] offset:128
	s_add_u32 s0, s68, 0x32000
	s_addc_u32 s1, s69, 0
	global_load_dword v160, v221, s[0:1]
	global_load_dword v182, v221, s[0:1] offset:128
	s_add_u32 s0, s68, 0x33000
	s_addc_u32 s1, s69, 0
	global_load_dword v161, v221, s[0:1]
	global_load_dword v183, v221, s[0:1] offset:128
	s_add_u32 s0, s68, 0x38000
	s_addc_u32 s1, s69, 0
	global_load_dword v162, v221, s[0:1]
	global_load_dword v184, v221, s[0:1] offset:128
	s_add_u32 s0, s68, 0x39000
	s_addc_u32 s1, s69, 0
	global_load_dword v163, v221, s[0:1]
	global_load_dword v185, v221, s[0:1] offset:128
	s_add_u32 s0, s68, 0x3a000
	s_addc_u32 s1, s69, 0
	global_load_dword v164, v221, s[0:1]
	global_load_dword v186, v221, s[0:1] offset:128
	s_add_u32 s0, s68, 0x3b000
	s_addc_u32 s1, s69, 0
	global_load_dword v165, v221, s[0:1]
	global_load_dword v187, v221, s[0:1] offset:128
	s_waitcnt vmcnt(32)
	v_fmac_f32_e32 v189, v112, v128
	v_fmac_f32_e32 v190, v113, v128
	v_fmac_f32_e32 v191, v114, v128
	v_fmac_f32_e32 v192, v115, v128
	v_fmac_f32_e32 v193, v116, v128
	v_fmac_f32_e32 v194, v117, v128
	v_fmac_f32_e32 v195, v118, v128
	v_fmac_f32_e32 v196, v119, v128
	v_fmac_f32_e32 v197, v120, v128
	v_fmac_f32_e32 v198, v121, v128
	v_fmac_f32_e32 v199, v122, v128
	v_fmac_f32_e32 v200, v123, v128
	v_fmac_f32_e32 v201, v124, v128
	v_fmac_f32_e32 v202, v125, v128
	v_fmac_f32_e32 v203, v126, v128
	v_fmac_f32_e32 v204, v127, v128
	v_fmac_f32_e32 v205, v96, v133
	v_fmac_f32_e32 v206, v97, v133
	v_fmac_f32_e32 v207, v98, v133
	v_fmac_f32_e32 v208, v99, v133
	v_fmac_f32_e32 v209, v100, v133
	v_fmac_f32_e32 v210, v101, v133
	v_fmac_f32_e32 v211, v102, v133
	v_fmac_f32_e32 v212, v103, v133
	v_fmac_f32_e32 v213, v104, v133
	v_fmac_f32_e32 v214, v105, v133
	v_fmac_f32_e32 v215, v106, v133
	v_fmac_f32_e32 v216, v107, v133
	v_fmac_f32_e32 v217, v108, v133
	v_fmac_f32_e32 v218, v109, v133
	v_fmac_f32_e32 v219, v110, v133
	v_fmac_f32_e32 v220, v111, v133
	s_add_u32 s0, s68, 0x40000
	s_addc_u32 s1, s69, 0
	global_load_dword v112, v221, s[0:1]
	global_load_dword v96, v221, s[0:1] offset:128
	s_add_u32 s0, s68, 0x41000
	s_addc_u32 s1, s69, 0
	global_load_dword v113, v221, s[0:1]
	global_load_dword v97, v221, s[0:1] offset:128
	s_add_u32 s0, s68, 0x42000
	s_addc_u32 s1, s69, 0
	global_load_dword v114, v221, s[0:1]
	global_load_dword v98, v221, s[0:1] offset:128
	s_add_u32 s0, s68, 0x43000
	s_addc_u32 s1, s69, 0
	global_load_dword v115, v221, s[0:1]
	global_load_dword v99, v221, s[0:1] offset:128
	s_add_u32 s0, s68, 0x48000
	s_addc_u32 s1, s69, 0
	global_load_dword v116, v221, s[0:1]
	global_load_dword v100, v221, s[0:1] offset:128
	s_add_u32 s0, s68, 0x49000
	s_addc_u32 s1, s69, 0
	global_load_dword v117, v221, s[0:1]
	global_load_dword v101, v221, s[0:1] offset:128
	s_add_u32 s0, s68, 0x4a000
	s_addc_u32 s1, s69, 0
	global_load_dword v118, v221, s[0:1]
	global_load_dword v102, v221, s[0:1] offset:128
	s_add_u32 s0, s68, 0x4b000
	s_addc_u32 s1, s69, 0
	global_load_dword v119, v221, s[0:1]
	global_load_dword v103, v221, s[0:1] offset:128
	s_add_u32 s0, s68, 0x50000
	s_addc_u32 s1, s69, 0
	global_load_dword v120, v221, s[0:1]
	global_load_dword v104, v221, s[0:1] offset:128
	s_add_u32 s0, s68, 0x51000
	s_addc_u32 s1, s69, 0
	global_load_dword v121, v221, s[0:1]
	global_load_dword v105, v221, s[0:1] offset:128
	s_add_u32 s0, s68, 0x52000
	s_addc_u32 s1, s69, 0
	global_load_dword v122, v221, s[0:1]
	global_load_dword v106, v221, s[0:1] offset:128
	s_add_u32 s0, s68, 0x53000
	s_addc_u32 s1, s69, 0
	global_load_dword v123, v221, s[0:1]
	global_load_dword v107, v221, s[0:1] offset:128
	s_add_u32 s0, s68, 0x58000
	s_addc_u32 s1, s69, 0
	global_load_dword v124, v221, s[0:1]
	global_load_dword v108, v221, s[0:1] offset:128
	s_add_u32 s0, s68, 0x59000
	s_addc_u32 s1, s69, 0
	global_load_dword v125, v221, s[0:1]
	global_load_dword v109, v221, s[0:1] offset:128
	s_add_u32 s0, s68, 0x5a000
	s_addc_u32 s1, s69, 0
	global_load_dword v126, v221, s[0:1]
	global_load_dword v110, v221, s[0:1] offset:128
	s_add_u32 s0, s68, 0x5b000
	s_addc_u32 s1, s69, 0
	global_load_dword v127, v221, s[0:1]
	global_load_dword v111, v221, s[0:1] offset:128
	s_waitcnt vmcnt(32)
	v_fmac_f32_e32 v150, v80, v128
	v_fmac_f32_e32 v151, v81, v128
	v_fmac_f32_e32 v152, v82, v128
	v_fmac_f32_e32 v153, v83, v128
	v_fmac_f32_e32 v154, v84, v128
	v_fmac_f32_e32 v155, v85, v128
	v_fmac_f32_e32 v156, v86, v128
	v_fmac_f32_e32 v157, v87, v128
	v_fmac_f32_e32 v158, v88, v128
	v_fmac_f32_e32 v159, v89, v128
	v_fmac_f32_e32 v160, v90, v128
	v_fmac_f32_e32 v161, v91, v128
	v_fmac_f32_e32 v162, v92, v128
	v_fmac_f32_e32 v163, v93, v128
	v_fmac_f32_e32 v164, v94, v128
	v_fmac_f32_e32 v165, v95, v128
	v_fmac_f32_e32 v172, v64, v133
	v_fmac_f32_e32 v173, v65, v133
	v_fmac_f32_e32 v174, v66, v133
	v_fmac_f32_e32 v175, v67, v133
	v_fmac_f32_e32 v176, v68, v133
	v_fmac_f32_e32 v177, v69, v133
	v_fmac_f32_e32 v178, v70, v133
	v_fmac_f32_e32 v179, v71, v133
	v_fmac_f32_e32 v180, v72, v133
	v_fmac_f32_e32 v181, v73, v133
	v_fmac_f32_e32 v182, v74, v133
	v_fmac_f32_e32 v183, v75, v133
	v_fmac_f32_e32 v184, v76, v133
	v_fmac_f32_e32 v185, v77, v133
	v_fmac_f32_e32 v186, v78, v133
	v_fmac_f32_e32 v187, v79, v133
	s_add_u32 s0, s68, 0x60000
	s_addc_u32 s1, s69, 0
	global_load_dword v80, v221, s[0:1]
	global_load_dword v64, v221, s[0:1] offset:128
	s_add_u32 s0, s68, 0x61000
	s_addc_u32 s1, s69, 0
	global_load_dword v81, v221, s[0:1]
	global_load_dword v65, v221, s[0:1] offset:128
	s_add_u32 s0, s68, 0x62000
	s_addc_u32 s1, s69, 0
	global_load_dword v82, v221, s[0:1]
	global_load_dword v66, v221, s[0:1] offset:128
	s_add_u32 s0, s68, 0x63000
	s_addc_u32 s1, s69, 0
	global_load_dword v83, v221, s[0:1]
	global_load_dword v67, v221, s[0:1] offset:128
	s_add_u32 s0, s68, 0x68000
	s_addc_u32 s1, s69, 0
	global_load_dword v84, v221, s[0:1]
	global_load_dword v68, v221, s[0:1] offset:128
	s_add_u32 s0, s68, 0x69000
	s_addc_u32 s1, s69, 0
	global_load_dword v85, v221, s[0:1]
	global_load_dword v69, v221, s[0:1] offset:128
	s_add_u32 s0, s68, 0x6a000
	s_addc_u32 s1, s69, 0
	global_load_dword v86, v221, s[0:1]
	global_load_dword v70, v221, s[0:1] offset:128
	s_add_u32 s0, s68, 0x6b000
	s_addc_u32 s1, s69, 0
	global_load_dword v87, v221, s[0:1]
	global_load_dword v71, v221, s[0:1] offset:128
	s_add_u32 s0, s68, 0x70000
	s_addc_u32 s1, s69, 0
	global_load_dword v88, v221, s[0:1]
	global_load_dword v72, v221, s[0:1] offset:128
	s_add_u32 s0, s68, 0x71000
	s_addc_u32 s1, s69, 0
	global_load_dword v89, v221, s[0:1]
	global_load_dword v73, v221, s[0:1] offset:128
	s_add_u32 s0, s68, 0x72000
	s_addc_u32 s1, s69, 0
	global_load_dword v90, v221, s[0:1]
	global_load_dword v74, v221, s[0:1] offset:128
	s_add_u32 s0, s68, 0x73000
	s_addc_u32 s1, s69, 0
	global_load_dword v91, v221, s[0:1]
	global_load_dword v75, v221, s[0:1] offset:128
	s_add_u32 s0, s68, 0x78000
	s_addc_u32 s1, s69, 0
	global_load_dword v92, v221, s[0:1]
	global_load_dword v76, v221, s[0:1] offset:128
	s_add_u32 s0, s68, 0x79000
	s_addc_u32 s1, s69, 0
	global_load_dword v93, v221, s[0:1]
	global_load_dword v77, v221, s[0:1] offset:128
	s_add_u32 s0, s68, 0x7a000
	s_addc_u32 s1, s69, 0
	global_load_dword v94, v221, s[0:1]
	global_load_dword v78, v221, s[0:1] offset:128
	s_add_u32 s0, s68, 0x7b000
	s_addc_u32 s1, s69, 0
	global_load_dword v95, v221, s[0:1]
	global_load_dword v79, v221, s[0:1] offset:128
	s_waitcnt vmcnt(32)
	v_fmac_f32_e32 v112, v48, v128
	v_fmac_f32_e32 v113, v49, v128
	v_fmac_f32_e32 v114, v50, v128
	v_fmac_f32_e32 v115, v51, v128
	v_fmac_f32_e32 v116, v52, v128
	v_fmac_f32_e32 v117, v53, v128
	v_fmac_f32_e32 v118, v54, v128
	v_fmac_f32_e32 v119, v55, v128
	v_fmac_f32_e32 v120, v56, v128
	v_fmac_f32_e32 v121, v57, v128
	v_fmac_f32_e32 v122, v58, v128
	v_fmac_f32_e32 v123, v59, v128
	v_fmac_f32_e32 v124, v60, v128
	v_fmac_f32_e32 v125, v61, v128
	v_fmac_f32_e32 v126, v62, v128
	v_fmac_f32_e32 v127, v63, v128
	v_fmac_f32_e32 v96, v32, v133
	v_fmac_f32_e32 v97, v33, v133
	v_fmac_f32_e32 v98, v34, v133
	v_fmac_f32_e32 v99, v35, v133
	v_fmac_f32_e32 v100, v36, v133
	v_fmac_f32_e32 v101, v37, v133
	v_fmac_f32_e32 v102, v38, v133
	v_fmac_f32_e32 v103, v39, v133
	v_fmac_f32_e32 v104, v40, v133
	v_fmac_f32_e32 v105, v41, v133
	v_fmac_f32_e32 v106, v42, v133
	v_fmac_f32_e32 v107, v43, v133
	v_fmac_f32_e32 v108, v44, v133
	v_fmac_f32_e32 v109, v45, v133
	v_fmac_f32_e32 v110, v46, v133
	v_fmac_f32_e32 v111, v47, v133
	s_waitcnt vmcnt(0)
	v_fmac_f32_e32 v80, v16, v128
	v_fmac_f32_e32 v81, v17, v128
	v_fmac_f32_e32 v82, v18, v128
	v_fmac_f32_e32 v83, v19, v128
	v_fmac_f32_e32 v84, v20, v128
	v_fmac_f32_e32 v85, v21, v128
	v_fmac_f32_e32 v86, v22, v128
	v_fmac_f32_e32 v87, v23, v128
	v_fmac_f32_e32 v88, v24, v128
	v_fmac_f32_e32 v89, v25, v128
	v_fmac_f32_e32 v90, v26, v128
	v_fmac_f32_e32 v91, v27, v128
	v_fmac_f32_e32 v92, v28, v128
	v_fmac_f32_e32 v93, v29, v128
	v_fmac_f32_e32 v94, v30, v128
	v_fmac_f32_e32 v95, v31, v128
	v_fmac_f32_e32 v64, v0, v133
	v_fmac_f32_e32 v65, v1, v133
	v_fmac_f32_e32 v66, v2, v133
	v_fmac_f32_e32 v67, v3, v133
	v_fmac_f32_e32 v68, v4, v133
	v_fmac_f32_e32 v69, v5, v133
	v_fmac_f32_e32 v70, v6, v133
	v_fmac_f32_e32 v71, v7, v133
	v_fmac_f32_e32 v72, v8, v133
	v_fmac_f32_e32 v73, v9, v133
	v_fmac_f32_e32 v74, v10, v133
	v_fmac_f32_e32 v75, v11, v133
	v_fmac_f32_e32 v76, v12, v133
	v_fmac_f32_e32 v77, v13, v133
	v_fmac_f32_e32 v78, v14, v133
	v_fmac_f32_e32 v79, v15, v133
	s_mov_b32 s0, s68
	s_mov_b32 s1, s69
	global_store_dword v221, v189, s[0:1]
	global_store_dword v221, v205, s[0:1] offset:128
	s_add_u32 s0, s68, 0x1000
	s_addc_u32 s1, s69, 0
	global_store_dword v221, v190, s[0:1]
	global_store_dword v221, v206, s[0:1] offset:128
	s_add_u32 s0, s68, 0x2000
	s_addc_u32 s1, s69, 0
	global_store_dword v221, v191, s[0:1]
	global_store_dword v221, v207, s[0:1] offset:128
	s_add_u32 s0, s68, 0x3000
	s_addc_u32 s1, s69, 0
	global_store_dword v221, v192, s[0:1]
	global_store_dword v221, v208, s[0:1] offset:128
	s_add_u32 s0, s68, 0x8000
	s_addc_u32 s1, s69, 0
	global_store_dword v221, v193, s[0:1]
	global_store_dword v221, v209, s[0:1] offset:128
	s_add_u32 s0, s68, 0x9000
	s_addc_u32 s1, s69, 0
	global_store_dword v221, v194, s[0:1]
	global_store_dword v221, v210, s[0:1] offset:128
	s_add_u32 s0, s68, 0xa000
	s_addc_u32 s1, s69, 0
	global_store_dword v221, v195, s[0:1]
	global_store_dword v221, v211, s[0:1] offset:128
	s_add_u32 s0, s68, 0xb000
	s_addc_u32 s1, s69, 0
	global_store_dword v221, v196, s[0:1]
	global_store_dword v221, v212, s[0:1] offset:128
	s_add_u32 s0, s68, 0x10000
	s_addc_u32 s1, s69, 0
	global_store_dword v221, v197, s[0:1]
	global_store_dword v221, v213, s[0:1] offset:128
	s_add_u32 s0, s68, 0x11000
	s_addc_u32 s1, s69, 0
	global_store_dword v221, v198, s[0:1]
	global_store_dword v221, v214, s[0:1] offset:128
	s_add_u32 s0, s68, 0x12000
	s_addc_u32 s1, s69, 0
	global_store_dword v221, v199, s[0:1]
	global_store_dword v221, v215, s[0:1] offset:128
	s_add_u32 s0, s68, 0x13000
	s_addc_u32 s1, s69, 0
	global_store_dword v221, v200, s[0:1]
	global_store_dword v221, v216, s[0:1] offset:128
	s_add_u32 s0, s68, 0x18000
	s_addc_u32 s1, s69, 0
	global_store_dword v221, v201, s[0:1]
	global_store_dword v221, v217, s[0:1] offset:128
	s_add_u32 s0, s68, 0x19000
	s_addc_u32 s1, s69, 0
	global_store_dword v221, v202, s[0:1]
	global_store_dword v221, v218, s[0:1] offset:128
	s_add_u32 s0, s68, 0x1a000
	s_addc_u32 s1, s69, 0
	global_store_dword v221, v203, s[0:1]
	global_store_dword v221, v219, s[0:1] offset:128
	s_add_u32 s0, s68, 0x1b000
	s_addc_u32 s1, s69, 0
	global_store_dword v221, v204, s[0:1]
	global_store_dword v221, v220, s[0:1] offset:128
	s_add_u32 s0, s68, 0x20000
	s_addc_u32 s1, s69, 0
	global_store_dword v221, v150, s[0:1]
	global_store_dword v221, v172, s[0:1] offset:128
	s_add_u32 s0, s68, 0x21000
	s_addc_u32 s1, s69, 0
	global_store_dword v221, v151, s[0:1]
	global_store_dword v221, v173, s[0:1] offset:128
	s_add_u32 s0, s68, 0x22000
	s_addc_u32 s1, s69, 0
	global_store_dword v221, v152, s[0:1]
	global_store_dword v221, v174, s[0:1] offset:128
	s_add_u32 s0, s68, 0x23000
	s_addc_u32 s1, s69, 0
	global_store_dword v221, v153, s[0:1]
	global_store_dword v221, v175, s[0:1] offset:128
	s_add_u32 s0, s68, 0x28000
	s_addc_u32 s1, s69, 0
	global_store_dword v221, v154, s[0:1]
	global_store_dword v221, v176, s[0:1] offset:128
	s_add_u32 s0, s68, 0x29000
	s_addc_u32 s1, s69, 0
	global_store_dword v221, v155, s[0:1]
	global_store_dword v221, v177, s[0:1] offset:128
	s_add_u32 s0, s68, 0x2a000
	s_addc_u32 s1, s69, 0
	global_store_dword v221, v156, s[0:1]
	global_store_dword v221, v178, s[0:1] offset:128
	s_add_u32 s0, s68, 0x2b000
	s_addc_u32 s1, s69, 0
	global_store_dword v221, v157, s[0:1]
	global_store_dword v221, v179, s[0:1] offset:128
	s_add_u32 s0, s68, 0x30000
	s_addc_u32 s1, s69, 0
	global_store_dword v221, v158, s[0:1]
	global_store_dword v221, v180, s[0:1] offset:128
	s_add_u32 s0, s68, 0x31000
	s_addc_u32 s1, s69, 0
	global_store_dword v221, v159, s[0:1]
	global_store_dword v221, v181, s[0:1] offset:128
	s_add_u32 s0, s68, 0x32000
	s_addc_u32 s1, s69, 0
	global_store_dword v221, v160, s[0:1]
	global_store_dword v221, v182, s[0:1] offset:128
	s_add_u32 s0, s68, 0x33000
	s_addc_u32 s1, s69, 0
	global_store_dword v221, v161, s[0:1]
	global_store_dword v221, v183, s[0:1] offset:128
	s_add_u32 s0, s68, 0x38000
	s_addc_u32 s1, s69, 0
	global_store_dword v221, v162, s[0:1]
	global_store_dword v221, v184, s[0:1] offset:128
	s_add_u32 s0, s68, 0x39000
	s_addc_u32 s1, s69, 0
	global_store_dword v221, v163, s[0:1]
	global_store_dword v221, v185, s[0:1] offset:128
	s_add_u32 s0, s68, 0x3a000
	s_addc_u32 s1, s69, 0
	global_store_dword v221, v164, s[0:1]
	global_store_dword v221, v186, s[0:1] offset:128
	s_add_u32 s0, s68, 0x3b000
	s_addc_u32 s1, s69, 0
	global_store_dword v221, v165, s[0:1]
	global_store_dword v221, v187, s[0:1] offset:128
	s_add_u32 s0, s68, 0x40000
	s_addc_u32 s1, s69, 0
	global_store_dword v221, v112, s[0:1]
	global_store_dword v221, v96, s[0:1] offset:128
	s_add_u32 s0, s68, 0x41000
	s_addc_u32 s1, s69, 0
	global_store_dword v221, v113, s[0:1]
	global_store_dword v221, v97, s[0:1] offset:128
	s_add_u32 s0, s68, 0x42000
	s_addc_u32 s1, s69, 0
	global_store_dword v221, v114, s[0:1]
	global_store_dword v221, v98, s[0:1] offset:128
	s_add_u32 s0, s68, 0x43000
	s_addc_u32 s1, s69, 0
	global_store_dword v221, v115, s[0:1]
	global_store_dword v221, v99, s[0:1] offset:128
	s_add_u32 s0, s68, 0x48000
	s_addc_u32 s1, s69, 0
	global_store_dword v221, v116, s[0:1]
	global_store_dword v221, v100, s[0:1] offset:128
	s_add_u32 s0, s68, 0x49000
	s_addc_u32 s1, s69, 0
	global_store_dword v221, v117, s[0:1]
	global_store_dword v221, v101, s[0:1] offset:128
	s_add_u32 s0, s68, 0x4a000
	s_addc_u32 s1, s69, 0
	global_store_dword v221, v118, s[0:1]
	global_store_dword v221, v102, s[0:1] offset:128
	s_add_u32 s0, s68, 0x4b000
	s_addc_u32 s1, s69, 0
	global_store_dword v221, v119, s[0:1]
	global_store_dword v221, v103, s[0:1] offset:128
	s_add_u32 s0, s68, 0x50000
	s_addc_u32 s1, s69, 0
	global_store_dword v221, v120, s[0:1]
	global_store_dword v221, v104, s[0:1] offset:128
	s_add_u32 s0, s68, 0x51000
	s_addc_u32 s1, s69, 0
	global_store_dword v221, v121, s[0:1]
	global_store_dword v221, v105, s[0:1] offset:128
	s_add_u32 s0, s68, 0x52000
	s_addc_u32 s1, s69, 0
	global_store_dword v221, v122, s[0:1]
	global_store_dword v221, v106, s[0:1] offset:128
	s_add_u32 s0, s68, 0x53000
	s_addc_u32 s1, s69, 0
	global_store_dword v221, v123, s[0:1]
	global_store_dword v221, v107, s[0:1] offset:128
	s_add_u32 s0, s68, 0x58000
	s_addc_u32 s1, s69, 0
	global_store_dword v221, v124, s[0:1]
	global_store_dword v221, v108, s[0:1] offset:128
	s_add_u32 s0, s68, 0x59000
	s_addc_u32 s1, s69, 0
	global_store_dword v221, v125, s[0:1]
	global_store_dword v221, v109, s[0:1] offset:128
	s_add_u32 s0, s68, 0x5a000
	s_addc_u32 s1, s69, 0
	global_store_dword v221, v126, s[0:1]
	global_store_dword v221, v110, s[0:1] offset:128
	s_add_u32 s0, s68, 0x5b000
	s_addc_u32 s1, s69, 0
	global_store_dword v221, v127, s[0:1]
	global_store_dword v221, v111, s[0:1] offset:128
	s_add_u32 s0, s68, 0x60000
	s_addc_u32 s1, s69, 0
	global_store_dword v221, v80, s[0:1]
	global_store_dword v221, v64, s[0:1] offset:128
	s_add_u32 s0, s68, 0x61000
	s_addc_u32 s1, s69, 0
	global_store_dword v221, v81, s[0:1]
	global_store_dword v221, v65, s[0:1] offset:128
	s_add_u32 s0, s68, 0x62000
	s_addc_u32 s1, s69, 0
	global_store_dword v221, v82, s[0:1]
	global_store_dword v221, v66, s[0:1] offset:128
	s_add_u32 s0, s68, 0x63000
	s_addc_u32 s1, s69, 0
	global_store_dword v221, v83, s[0:1]
	global_store_dword v221, v67, s[0:1] offset:128
	s_add_u32 s0, s68, 0x68000
	s_addc_u32 s1, s69, 0
	global_store_dword v221, v84, s[0:1]
	global_store_dword v221, v68, s[0:1] offset:128
	s_add_u32 s0, s68, 0x69000
	s_addc_u32 s1, s69, 0
	global_store_dword v221, v85, s[0:1]
	global_store_dword v221, v69, s[0:1] offset:128
	s_add_u32 s0, s68, 0x6a000
	s_addc_u32 s1, s69, 0
	global_store_dword v221, v86, s[0:1]
	global_store_dword v221, v70, s[0:1] offset:128
	s_add_u32 s0, s68, 0x6b000
	s_addc_u32 s1, s69, 0
	global_store_dword v221, v87, s[0:1]
	global_store_dword v221, v71, s[0:1] offset:128
	s_add_u32 s0, s68, 0x70000
	s_addc_u32 s1, s69, 0
	global_store_dword v221, v88, s[0:1]
	global_store_dword v221, v72, s[0:1] offset:128
	s_add_u32 s0, s68, 0x71000
	s_addc_u32 s1, s69, 0
	global_store_dword v221, v89, s[0:1]
	global_store_dword v221, v73, s[0:1] offset:128
	s_add_u32 s0, s68, 0x72000
	s_addc_u32 s1, s69, 0
	global_store_dword v221, v90, s[0:1]
	global_store_dword v221, v74, s[0:1] offset:128
	s_add_u32 s0, s68, 0x73000
	s_addc_u32 s1, s69, 0
	global_store_dword v221, v91, s[0:1]
	global_store_dword v221, v75, s[0:1] offset:128
	s_add_u32 s0, s68, 0x78000
	s_addc_u32 s1, s69, 0
	global_store_dword v221, v92, s[0:1]
	global_store_dword v221, v76, s[0:1] offset:128
	s_add_u32 s0, s68, 0x79000
	s_addc_u32 s1, s69, 0
	global_store_dword v221, v93, s[0:1]
	global_store_dword v221, v77, s[0:1] offset:128
	s_add_u32 s0, s68, 0x7a000
	s_addc_u32 s1, s69, 0
	global_store_dword v221, v94, s[0:1]
	global_store_dword v221, v78, s[0:1] offset:128
	s_add_u32 s0, s68, 0x7b000
	s_addc_u32 s1, s69, 0
	global_store_dword v221, v95, s[0:1]
	global_store_dword v221, v79, s[0:1] offset:128
	s_andn2_b64 exec, exec, s[46:47]
	s_cbranch_execz .LBB0_237

.LBB0_280:
	s_or_b64 exec, exec, s[0:1]
	s_mov_b64 s[38:39], s[68:69]
	s_and_b64 vcc, exec, s[18:19]
	s_cbranch_vccnz .Lg4_src_done
	v_readfirstlane_b32 s0, v167
	s_nop 3
	s_cmp_lt_i32 s0, s33
	s_cselect_b32 s38, s76, s78
	s_cselect_b32 s39, s77, s79
	s_cbranch_scc1 .Lg4_src_done
	s_sub_u32 s38, s38, 0x2000000
	s_subb_u32 s39, s39, 0
.Lg4_src_done:
	v_add_u32_e32 v222, v167, v235
	v_or_b32_e32 v223, v166, v234
	v_lshlrev_b32_e32 v221, 12, v222
	v_lshl_add_u32 v221, v223, 2, v221
	s_mov_b32 s0, s38
	s_mov_b32 s1, s39
	global_load_dword v189, v221, s[0:1]
	global_load_dword v205, v221, s[0:1] offset:128
	s_add_u32 s0, s38, 0x1000
	s_addc_u32 s1, s39, 0
	global_load_dword v190, v221, s[0:1]
	global_load_dword v206, v221, s[0:1] offset:128
	s_add_u32 s0, s38, 0x2000
	s_addc_u32 s1, s39, 0
	global_load_dword v191, v221, s[0:1]
	global_load_dword v207, v221, s[0:1] offset:128
	s_add_u32 s0, s38, 0x3000
	s_addc_u32 s1, s39, 0
	global_load_dword v192, v221, s[0:1]
	global_load_dword v208, v221, s[0:1] offset:128
	s_add_u32 s0, s38, 0x8000
	s_addc_u32 s1, s39, 0
	global_load_dword v193, v221, s[0:1]
	global_load_dword v209, v221, s[0:1] offset:128
	s_add_u32 s0, s38, 0x9000
	s_addc_u32 s1, s39, 0
	global_load_dword v194, v221, s[0:1]
	global_load_dword v210, v221, s[0:1] offset:128
	s_add_u32 s0, s38, 0xa000
	s_addc_u32 s1, s39, 0
	global_load_dword v195, v221, s[0:1]
	global_load_dword v211, v221, s[0:1] offset:128
	s_add_u32 s0, s38, 0xb000
	s_addc_u32 s1, s39, 0
	global_load_dword v196, v221, s[0:1]
	global_load_dword v212, v221, s[0:1] offset:128
	s_add_u32 s0, s38, 0x10000
	s_addc_u32 s1, s39, 0
	global_load_dword v197, v221, s[0:1]
	global_load_dword v213, v221, s[0:1] offset:128
	s_add_u32 s0, s38, 0x11000
	s_addc_u32 s1, s39, 0
	global_load_dword v198, v221, s[0:1]
	global_load_dword v214, v221, s[0:1] offset:128
	s_add_u32 s0, s38, 0x12000
	s_addc_u32 s1, s39, 0
	global_load_dword v199, v221, s[0:1]
	global_load_dword v215, v221, s[0:1] offset:128
	s_add_u32 s0, s38, 0x13000
	s_addc_u32 s1, s39, 0
	global_load_dword v200, v221, s[0:1]
	global_load_dword v216, v221, s[0:1] offset:128
	s_add_u32 s0, s38, 0x18000
	s_addc_u32 s1, s39, 0
	global_load_dword v201, v221, s[0:1]
	global_load_dword v217, v221, s[0:1] offset:128
	s_add_u32 s0, s38, 0x19000
	s_addc_u32 s1, s39, 0
	global_load_dword v202, v221, s[0:1]
	global_load_dword v218, v221, s[0:1] offset:128
	s_add_u32 s0, s38, 0x1a000
	s_addc_u32 s1, s39, 0
	global_load_dword v203, v221, s[0:1]
	global_load_dword v219, v221, s[0:1] offset:128
	s_add_u32 s0, s38, 0x1b000
	s_addc_u32 s1, s39, 0
	global_load_dword v204, v221, s[0:1]
	global_load_dword v220, v221, s[0:1] offset:128
	v_add_u32_e32 v131, v130, v169
	ds_read_b128 v[132:135], v131
	ds_read_b128 v[136:139], v131 offset:4096
	ds_read_b128 v[140:143], v131 offset:8192
	ds_read_b128 v[144:147], v131 offset:12288
	v_add_u32_e32 v131, v128, v169
	ds_read_b128 v[148:151], v131 offset:32768
	ds_read_b128 v[152:155], v131 offset:36864
	s_setprio 1
	s_waitcnt lgkmcnt(0)
	v_mfma_f32_32x32x16_bf16 v[112:127], v[132:135], v[148:151], v[112:127]
	v_mfma_f32_32x32x16_bf16 v[96:111], v[132:135], v[152:155], v[96:111]
	v_mfma_f32_32x32x16_bf16 v[80:95], v[136:139], v[148:151], v[80:95]
	v_mfma_f32_32x32x16_bf16 v[64:79], v[136:139], v[152:155], v[64:79]
	v_mfma_f32_32x32x16_bf16 v[48:63], v[140:143], v[148:151], v[48:63]
	v_mfma_f32_32x32x16_bf16 v[32:47], v[140:143], v[152:155], v[32:47]
	v_mfma_f32_32x32x16_bf16 v[16:31], v[144:147], v[148:151], v[16:31]
	v_mfma_f32_32x32x16_bf16 v[0:15], v[144:147], v[152:155], v[0:15]
	s_setprio 0
	v_add_u32_e32 v142, v130, v168
	ds_read_b128 v[130:133], v142
	ds_read_b128 v[134:137], v142 offset:4096
	ds_read_b128 v[138:141], v142 offset:8192
	ds_read_b128 v[142:145], v142 offset:12288
	v_add_u32_e32 v128, v128, v168
	ds_read_b128 v[146:149], v128 offset:32768
	ds_read_b128 v[150:153], v128 offset:36864
	s_setprio 1
	s_waitcnt lgkmcnt(0)
	v_mfma_f32_32x32x16_bf16 v[112:127], v[130:133], v[146:149], v[112:127]
	v_mfma_f32_32x32x16_bf16 v[96:111], v[130:133], v[150:153], v[96:111]
	v_mfma_f32_32x32x16_bf16 v[80:95], v[134:137], v[146:149], v[80:95]
	v_mfma_f32_32x32x16_bf16 v[64:79], v[134:137], v[150:153], v[64:79]
	v_mfma_f32_32x32x16_bf16 v[48:63], v[138:141], v[146:149], v[48:63]
	v_mfma_f32_32x32x16_bf16 v[32:47], v[138:141], v[150:153], v[32:47]
	v_mfma_f32_32x32x16_bf16 v[16:31], v[142:145], v[146:149], v[16:31]
	v_mfma_f32_32x32x16_bf16 v[0:15], v[142:145], v[150:153], v[0:15]
	s_setprio 0
	v_or_b32_e32 v144, v166, v234
	v_readlane_b32 s1, v254, 62
	s_movk_i32 s0, 0x1fff
	v_add_u32_e32 v128, 0xffffe000, v167
	v_cmp_lt_i32_e32 vcc, s0, v167
	v_lshrrev_b32_e32 v128, 10, v128
	v_add_u32_e32 v128, 1, v128
	v_cndmask_b32_e32 v128, 0, v128, vcc
	v_mov_b64_e32 v[130:131], s[66:67]
	v_add_u32_e32 v128, s1, v128
	s_movk_i32 s0, 0x6000
	v_mad_u64_u32 v[130:131], s[0:1], v128, s0, v[130:131]
	s_mov_b64 s[0:1], 0x2000
	v_lshl_add_u64 v[130:131], v[130:131], 0, s[0:1]
	v_mov_b32_e32 v135, 0
	v_lshlrev_b32_e32 v134, 2, v144
	v_lshl_add_u64 v[130:131], v[130:131], 0, v[134:135]
	global_load_dword v128, v[130:131], off
	global_load_dword v133, v[130:131], off offset:128
	s_add_u32 s0, s38, 0x20000
	s_addc_u32 s1, s39, 0
	global_load_dword v150, v221, s[0:1]
	global_load_dword v172, v221, s[0:1] offset:128
	s_add_u32 s0, s38, 0x21000
	s_addc_u32 s1, s39, 0
	global_load_dword v151, v221, s[0:1]
	global_load_dword v173, v221, s[0:1] offset:128
	s_add_u32 s0, s38, 0x22000
	s_addc_u32 s1, s39, 0
	global_load_dword v152, v221, s[0:1]
	global_load_dword v174, v221, s[0:1] offset:128
	s_add_u32 s0, s38, 0x23000
	s_addc_u32 s1, s39, 0
	global_load_dword v153, v221, s[0:1]
	global_load_dword v175, v221, s[0:1] offset:128
	s_add_u32 s0, s38, 0x28000
	s_addc_u32 s1, s39, 0
	global_load_dword v154, v221, s[0:1]
	global_load_dword v176, v221, s[0:1] offset:128
	s_add_u32 s0, s38, 0x29000
	s_addc_u32 s1, s39, 0
	global_load_dword v155, v221, s[0:1]
	global_load_dword v177, v221, s[0:1] offset:128
	s_add_u32 s0, s38, 0x2a000
	s_addc_u32 s1, s39, 0
	global_load_dword v156, v221, s[0:1]
	global_load_dword v178, v221, s[0:1] offset:128
	s_add_u32 s0, s38, 0x2b000
	s_addc_u32 s1, s39, 0
	global_load_dword v157, v221, s[0:1]
	global_load_dword v179, v221, s[0:1] offset:128
	s_add_u32 s0, s38, 0x30000
	s_addc_u32 s1, s39, 0
	global_load_dword v158, v221, s[0:1]
	global_load_dword v180, v221, s[0:1] offset:128
	s_add_u32 s0, s38, 0x31000
	s_addc_u32 s1, s39, 0
	global_load_dword v159, v221, s[0:1]
	global_load_dword v181, v221, s[0:1] offset:128
	s_add_u32 s0, s38, 0x32000
	s_addc_u32 s1, s39, 0
	global_load_dword v160, v221, s[0:1]
	global_load_dword v182, v221, s[0:1] offset:128
	s_add_u32 s0, s38, 0x33000
	s_addc_u32 s1, s39, 0
	global_load_dword v161, v221, s[0:1]
	global_load_dword v183, v221, s[0:1] offset:128
	s_add_u32 s0, s38, 0x38000
	s_addc_u32 s1, s39, 0
	global_load_dword v162, v221, s[0:1]
	global_load_dword v184, v221, s[0:1] offset:128
	s_add_u32 s0, s38, 0x39000
	s_addc_u32 s1, s39, 0
	global_load_dword v163, v221, s[0:1]
	global_load_dword v185, v221, s[0:1] offset:128
	s_add_u32 s0, s38, 0x3a000
	s_addc_u32 s1, s39, 0
	global_load_dword v164, v221, s[0:1]
	global_load_dword v186, v221, s[0:1] offset:128
	s_add_u32 s0, s38, 0x3b000
	s_addc_u32 s1, s39, 0
	global_load_dword v165, v221, s[0:1]
	global_load_dword v187, v221, s[0:1] offset:128
	s_waitcnt vmcnt(32)
	v_fmac_f32_e32 v189, v112, v128
	v_fmac_f32_e32 v190, v113, v128
	v_fmac_f32_e32 v191, v114, v128
	v_fmac_f32_e32 v192, v115, v128
	v_fmac_f32_e32 v193, v116, v128
	v_fmac_f32_e32 v194, v117, v128
	v_fmac_f32_e32 v195, v118, v128
	v_fmac_f32_e32 v196, v119, v128
	v_fmac_f32_e32 v197, v120, v128
	v_fmac_f32_e32 v198, v121, v128
	v_fmac_f32_e32 v199, v122, v128
	v_fmac_f32_e32 v200, v123, v128
	v_fmac_f32_e32 v201, v124, v128
	v_fmac_f32_e32 v202, v125, v128
	v_fmac_f32_e32 v203, v126, v128
	v_fmac_f32_e32 v204, v127, v128
	v_fmac_f32_e32 v205, v96, v133
	v_fmac_f32_e32 v206, v97, v133
	v_fmac_f32_e32 v207, v98, v133
	v_fmac_f32_e32 v208, v99, v133
	v_fmac_f32_e32 v209, v100, v133
	v_fmac_f32_e32 v210, v101, v133
	v_fmac_f32_e32 v211, v102, v133
	v_fmac_f32_e32 v212, v103, v133
	v_fmac_f32_e32 v213, v104, v133
	v_fmac_f32_e32 v214, v105, v133
	v_fmac_f32_e32 v215, v106, v133
	v_fmac_f32_e32 v216, v107, v133
	v_fmac_f32_e32 v217, v108, v133
	v_fmac_f32_e32 v218, v109, v133
	v_fmac_f32_e32 v219, v110, v133
	v_fmac_f32_e32 v220, v111, v133
	s_add_u32 s0, s38, 0x40000
	s_addc_u32 s1, s39, 0
	global_load_dword v112, v221, s[0:1]
	global_load_dword v96, v221, s[0:1] offset:128
	s_add_u32 s0, s38, 0x41000
	s_addc_u32 s1, s39, 0
	global_load_dword v113, v221, s[0:1]
	global_load_dword v97, v221, s[0:1] offset:128
	s_add_u32 s0, s38, 0x42000
	s_addc_u32 s1, s39, 0
	global_load_dword v114, v221, s[0:1]
	global_load_dword v98, v221, s[0:1] offset:128
	s_add_u32 s0, s38, 0x43000
	s_addc_u32 s1, s39, 0
	global_load_dword v115, v221, s[0:1]
	global_load_dword v99, v221, s[0:1] offset:128
	s_add_u32 s0, s38, 0x48000
	s_addc_u32 s1, s39, 0
	global_load_dword v116, v221, s[0:1]
	global_load_dword v100, v221, s[0:1] offset:128
	s_add_u32 s0, s38, 0x49000
	s_addc_u32 s1, s39, 0
	global_load_dword v117, v221, s[0:1]
	global_load_dword v101, v221, s[0:1] offset:128
	s_add_u32 s0, s38, 0x4a000
	s_addc_u32 s1, s39, 0
	global_load_dword v118, v221, s[0:1]
	global_load_dword v102, v221, s[0:1] offset:128
	s_add_u32 s0, s38, 0x4b000
	s_addc_u32 s1, s39, 0
	global_load_dword v119, v221, s[0:1]
	global_load_dword v103, v221, s[0:1] offset:128
	s_add_u32 s0, s38, 0x50000
	s_addc_u32 s1, s39, 0
	global_load_dword v120, v221, s[0:1]
	global_load_dword v104, v221, s[0:1] offset:128
	s_add_u32 s0, s38, 0x51000
	s_addc_u32 s1, s39, 0
	global_load_dword v121, v221, s[0:1]
	global_load_dword v105, v221, s[0:1] offset:128
	s_add_u32 s0, s38, 0x52000
	s_addc_u32 s1, s39, 0
	global_load_dword v122, v221, s[0:1]
	global_load_dword v106, v221, s[0:1] offset:128
	s_add_u32 s0, s38, 0x53000
	s_addc_u32 s1, s39, 0
	global_load_dword v123, v221, s[0:1]
	global_load_dword v107, v221, s[0:1] offset:128
	s_add_u32 s0, s38, 0x58000
	s_addc_u32 s1, s39, 0
	global_load_dword v124, v221, s[0:1]
	global_load_dword v108, v221, s[0:1] offset:128
	s_add_u32 s0, s38, 0x59000
	s_addc_u32 s1, s39, 0
	global_load_dword v125, v221, s[0:1]
	global_load_dword v109, v221, s[0:1] offset:128
	s_add_u32 s0, s38, 0x5a000
	s_addc_u32 s1, s39, 0
	global_load_dword v126, v221, s[0:1]
	global_load_dword v110, v221, s[0:1] offset:128
	s_add_u32 s0, s38, 0x5b000
	s_addc_u32 s1, s39, 0
	global_load_dword v127, v221, s[0:1]
	global_load_dword v111, v221, s[0:1] offset:128
	s_waitcnt vmcnt(32)
	v_fmac_f32_e32 v150, v80, v128
	v_fmac_f32_e32 v151, v81, v128
	v_fmac_f32_e32 v152, v82, v128
	v_fmac_f32_e32 v153, v83, v128
	v_fmac_f32_e32 v154, v84, v128
	v_fmac_f32_e32 v155, v85, v128
	v_fmac_f32_e32 v156, v86, v128
	v_fmac_f32_e32 v157, v87, v128
	v_fmac_f32_e32 v158, v88, v128
	v_fmac_f32_e32 v159, v89, v128
	v_fmac_f32_e32 v160, v90, v128
	v_fmac_f32_e32 v161, v91, v128
	v_fmac_f32_e32 v162, v92, v128
	v_fmac_f32_e32 v163, v93, v128
	v_fmac_f32_e32 v164, v94, v128
	v_fmac_f32_e32 v165, v95, v128
	v_fmac_f32_e32 v172, v64, v133
	v_fmac_f32_e32 v173, v65, v133
	v_fmac_f32_e32 v174, v66, v133
	v_fmac_f32_e32 v175, v67, v133
	v_fmac_f32_e32 v176, v68, v133
	v_fmac_f32_e32 v177, v69, v133
	v_fmac_f32_e32 v178, v70, v133
	v_fmac_f32_e32 v179, v71, v133
	v_fmac_f32_e32 v180, v72, v133
	v_fmac_f32_e32 v181, v73, v133
	v_fmac_f32_e32 v182, v74, v133
	v_fmac_f32_e32 v183, v75, v133
	v_fmac_f32_e32 v184, v76, v133
	v_fmac_f32_e32 v185, v77, v133
	v_fmac_f32_e32 v186, v78, v133
	v_fmac_f32_e32 v187, v79, v133
	s_add_u32 s0, s38, 0x60000
	s_addc_u32 s1, s39, 0
	global_load_dword v80, v221, s[0:1]
	global_load_dword v64, v221, s[0:1] offset:128
	s_add_u32 s0, s38, 0x61000
	s_addc_u32 s1, s39, 0
	global_load_dword v81, v221, s[0:1]
	global_load_dword v65, v221, s[0:1] offset:128
	s_add_u32 s0, s38, 0x62000
	s_addc_u32 s1, s39, 0
	global_load_dword v82, v221, s[0:1]
	global_load_dword v66, v221, s[0:1] offset:128
	s_add_u32 s0, s38, 0x63000
	s_addc_u32 s1, s39, 0
	global_load_dword v83, v221, s[0:1]
	global_load_dword v67, v221, s[0:1] offset:128
	s_add_u32 s0, s38, 0x68000
	s_addc_u32 s1, s39, 0
	global_load_dword v84, v221, s[0:1]
	global_load_dword v68, v221, s[0:1] offset:128
	s_add_u32 s0, s38, 0x69000
	s_addc_u32 s1, s39, 0
	global_load_dword v85, v221, s[0:1]
	global_load_dword v69, v221, s[0:1] offset:128
	s_add_u32 s0, s38, 0x6a000
	s_addc_u32 s1, s39, 0
	global_load_dword v86, v221, s[0:1]
	global_load_dword v70, v221, s[0:1] offset:128
	s_add_u32 s0, s38, 0x6b000
	s_addc_u32 s1, s39, 0
	global_load_dword v87, v221, s[0:1]
	global_load_dword v71, v221, s[0:1] offset:128
	s_add_u32 s0, s38, 0x70000
	s_addc_u32 s1, s39, 0
	global_load_dword v88, v221, s[0:1]
	global_load_dword v72, v221, s[0:1] offset:128
	s_add_u32 s0, s38, 0x71000
	s_addc_u32 s1, s39, 0
	global_load_dword v89, v221, s[0:1]
	global_load_dword v73, v221, s[0:1] offset:128
	s_add_u32 s0, s38, 0x72000
	s_addc_u32 s1, s39, 0
	global_load_dword v90, v221, s[0:1]
	global_load_dword v74, v221, s[0:1] offset:128
	s_add_u32 s0, s38, 0x73000
	s_addc_u32 s1, s39, 0
	global_load_dword v91, v221, s[0:1]
	global_load_dword v75, v221, s[0:1] offset:128
	s_add_u32 s0, s38, 0x78000
	s_addc_u32 s1, s39, 0
	global_load_dword v92, v221, s[0:1]
	global_load_dword v76, v221, s[0:1] offset:128
	s_add_u32 s0, s38, 0x79000
	s_addc_u32 s1, s39, 0
	global_load_dword v93, v221, s[0:1]
	global_load_dword v77, v221, s[0:1] offset:128
	s_add_u32 s0, s38, 0x7a000
	s_addc_u32 s1, s39, 0
	global_load_dword v94, v221, s[0:1]
	global_load_dword v78, v221, s[0:1] offset:128
	s_add_u32 s0, s38, 0x7b000
	s_addc_u32 s1, s39, 0
	global_load_dword v95, v221, s[0:1]
	global_load_dword v79, v221, s[0:1] offset:128
	s_waitcnt vmcnt(32)
	v_fmac_f32_e32 v112, v48, v128
	v_fmac_f32_e32 v113, v49, v128
	v_fmac_f32_e32 v114, v50, v128
	v_fmac_f32_e32 v115, v51, v128
	v_fmac_f32_e32 v116, v52, v128
	v_fmac_f32_e32 v117, v53, v128
	v_fmac_f32_e32 v118, v54, v128
	v_fmac_f32_e32 v119, v55, v128
	v_fmac_f32_e32 v120, v56, v128
	v_fmac_f32_e32 v121, v57, v128
	v_fmac_f32_e32 v122, v58, v128
	v_fmac_f32_e32 v123, v59, v128
	v_fmac_f32_e32 v124, v60, v128
	v_fmac_f32_e32 v125, v61, v128
	v_fmac_f32_e32 v126, v62, v128
	v_fmac_f32_e32 v127, v63, v128
	v_fmac_f32_e32 v96, v32, v133
	v_fmac_f32_e32 v97, v33, v133
	v_fmac_f32_e32 v98, v34, v133
	v_fmac_f32_e32 v99, v35, v133
	v_fmac_f32_e32 v100, v36, v133
	v_fmac_f32_e32 v101, v37, v133
	v_fmac_f32_e32 v102, v38, v133
	v_fmac_f32_e32 v103, v39, v133
	v_fmac_f32_e32 v104, v40, v133
	v_fmac_f32_e32 v105, v41, v133
	v_fmac_f32_e32 v106, v42, v133
	v_fmac_f32_e32 v107, v43, v133
	v_fmac_f32_e32 v108, v44, v133
	v_fmac_f32_e32 v109, v45, v133
	v_fmac_f32_e32 v110, v46, v133
	v_fmac_f32_e32 v111, v47, v133
	s_waitcnt vmcnt(0)
	v_fmac_f32_e32 v80, v16, v128
	v_fmac_f32_e32 v81, v17, v128
	v_fmac_f32_e32 v82, v18, v128
	v_fmac_f32_e32 v83, v19, v128
	v_fmac_f32_e32 v84, v20, v128
	v_fmac_f32_e32 v85, v21, v128
	v_fmac_f32_e32 v86, v22, v128
	v_fmac_f32_e32 v87, v23, v128
	v_fmac_f32_e32 v88, v24, v128
	v_fmac_f32_e32 v89, v25, v128
	v_fmac_f32_e32 v90, v26, v128
	v_fmac_f32_e32 v91, v27, v128
	v_fmac_f32_e32 v92, v28, v128
	v_fmac_f32_e32 v93, v29, v128
	v_fmac_f32_e32 v94, v30, v128
	v_fmac_f32_e32 v95, v31, v128
	v_fmac_f32_e32 v64, v0, v133
	v_fmac_f32_e32 v65, v1, v133
	v_fmac_f32_e32 v66, v2, v133
	v_fmac_f32_e32 v67, v3, v133
	v_fmac_f32_e32 v68, v4, v133
	v_fmac_f32_e32 v69, v5, v133
	v_fmac_f32_e32 v70, v6, v133
	v_fmac_f32_e32 v71, v7, v133
	v_fmac_f32_e32 v72, v8, v133
	v_fmac_f32_e32 v73, v9, v133
	v_fmac_f32_e32 v74, v10, v133
	v_fmac_f32_e32 v75, v11, v133
	v_fmac_f32_e32 v76, v12, v133
	v_fmac_f32_e32 v77, v13, v133
	v_fmac_f32_e32 v78, v14, v133
	v_fmac_f32_e32 v79, v15, v133
	s_mov_b32 s0, s68
	s_mov_b32 s1, s69
	global_store_dword v221, v189, s[0:1]
	global_store_dword v221, v205, s[0:1] offset:128
	s_add_u32 s0, s68, 0x1000
	s_addc_u32 s1, s69, 0
	global_store_dword v221, v190, s[0:1]
	global_store_dword v221, v206, s[0:1] offset:128
	s_add_u32 s0, s68, 0x2000
	s_addc_u32 s1, s69, 0
	global_store_dword v221, v191, s[0:1]
	global_store_dword v221, v207, s[0:1] offset:128
	s_add_u32 s0, s68, 0x3000
	s_addc_u32 s1, s69, 0
	global_store_dword v221, v192, s[0:1]
	global_store_dword v221, v208, s[0:1] offset:128
	s_add_u32 s0, s68, 0x8000
	s_addc_u32 s1, s69, 0
	global_store_dword v221, v193, s[0:1]
	global_store_dword v221, v209, s[0:1] offset:128
	s_add_u32 s0, s68, 0x9000
	s_addc_u32 s1, s69, 0
	global_store_dword v221, v194, s[0:1]
	global_store_dword v221, v210, s[0:1] offset:128
	s_add_u32 s0, s68, 0xa000
	s_addc_u32 s1, s69, 0
	global_store_dword v221, v195, s[0:1]
	global_store_dword v221, v211, s[0:1] offset:128
	s_add_u32 s0, s68, 0xb000
	s_addc_u32 s1, s69, 0
	global_store_dword v221, v196, s[0:1]
	global_store_dword v221, v212, s[0:1] offset:128
	s_add_u32 s0, s68, 0x10000
	s_addc_u32 s1, s69, 0
	global_store_dword v221, v197, s[0:1]
	global_store_dword v221, v213, s[0:1] offset:128
	s_add_u32 s0, s68, 0x11000
	s_addc_u32 s1, s69, 0
	global_store_dword v221, v198, s[0:1]
	global_store_dword v221, v214, s[0:1] offset:128
	s_add_u32 s0, s68, 0x12000
	s_addc_u32 s1, s69, 0
	global_store_dword v221, v199, s[0:1]
	global_store_dword v221, v215, s[0:1] offset:128
	s_add_u32 s0, s68, 0x13000
	s_addc_u32 s1, s69, 0
	global_store_dword v221, v200, s[0:1]
	global_store_dword v221, v216, s[0:1] offset:128
	s_add_u32 s0, s68, 0x18000
	s_addc_u32 s1, s69, 0
	global_store_dword v221, v201, s[0:1]
	global_store_dword v221, v217, s[0:1] offset:128
	s_add_u32 s0, s68, 0x19000
	s_addc_u32 s1, s69, 0
	global_store_dword v221, v202, s[0:1]
	global_store_dword v221, v218, s[0:1] offset:128
	s_add_u32 s0, s68, 0x1a000
	s_addc_u32 s1, s69, 0
	global_store_dword v221, v203, s[0:1]
	global_store_dword v221, v219, s[0:1] offset:128
	s_add_u32 s0, s68, 0x1b000
	s_addc_u32 s1, s69, 0
	global_store_dword v221, v204, s[0:1]
	global_store_dword v221, v220, s[0:1] offset:128
	s_add_u32 s0, s68, 0x20000
	s_addc_u32 s1, s69, 0
	global_store_dword v221, v150, s[0:1]
	global_store_dword v221, v172, s[0:1] offset:128
	s_add_u32 s0, s68, 0x21000
	s_addc_u32 s1, s69, 0
	global_store_dword v221, v151, s[0:1]
	global_store_dword v221, v173, s[0:1] offset:128
	s_add_u32 s0, s68, 0x22000
	s_addc_u32 s1, s69, 0
	global_store_dword v221, v152, s[0:1]
	global_store_dword v221, v174, s[0:1] offset:128
	s_add_u32 s0, s68, 0x23000
	s_addc_u32 s1, s69, 0
	global_store_dword v221, v153, s[0:1]
	global_store_dword v221, v175, s[0:1] offset:128
	s_add_u32 s0, s68, 0x28000
	s_addc_u32 s1, s69, 0
	global_store_dword v221, v154, s[0:1]
	global_store_dword v221, v176, s[0:1] offset:128
	s_add_u32 s0, s68, 0x29000
	s_addc_u32 s1, s69, 0
	global_store_dword v221, v155, s[0:1]
	global_store_dword v221, v177, s[0:1] offset:128
	s_add_u32 s0, s68, 0x2a000
	s_addc_u32 s1, s69, 0
	global_store_dword v221, v156, s[0:1]
	global_store_dword v221, v178, s[0:1] offset:128
	s_add_u32 s0, s68, 0x2b000
	s_addc_u32 s1, s69, 0
	global_store_dword v221, v157, s[0:1]
	global_store_dword v221, v179, s[0:1] offset:128
	s_add_u32 s0, s68, 0x30000
	s_addc_u32 s1, s69, 0
	global_store_dword v221, v158, s[0:1]
	global_store_dword v221, v180, s[0:1] offset:128
	s_add_u32 s0, s68, 0x31000
	s_addc_u32 s1, s69, 0
	global_store_dword v221, v159, s[0:1]
	global_store_dword v221, v181, s[0:1] offset:128
	s_add_u32 s0, s68, 0x32000
	s_addc_u32 s1, s69, 0
	global_store_dword v221, v160, s[0:1]
	global_store_dword v221, v182, s[0:1] offset:128
	s_add_u32 s0, s68, 0x33000
	s_addc_u32 s1, s69, 0
	global_store_dword v221, v161, s[0:1]
	global_store_dword v221, v183, s[0:1] offset:128
	s_add_u32 s0, s68, 0x38000
	s_addc_u32 s1, s69, 0
	global_store_dword v221, v162, s[0:1]
	global_store_dword v221, v184, s[0:1] offset:128
	s_add_u32 s0, s68, 0x39000
	s_addc_u32 s1, s69, 0
	global_store_dword v221, v163, s[0:1]
	global_store_dword v221, v185, s[0:1] offset:128
	s_add_u32 s0, s68, 0x3a000
	s_addc_u32 s1, s69, 0
	global_store_dword v221, v164, s[0:1]
	global_store_dword v221, v186, s[0:1] offset:128
	s_add_u32 s0, s68, 0x3b000
	s_addc_u32 s1, s69, 0
	global_store_dword v221, v165, s[0:1]
	global_store_dword v221, v187, s[0:1] offset:128
	s_add_u32 s0, s68, 0x40000
	s_addc_u32 s1, s69, 0
	global_store_dword v221, v112, s[0:1]
	global_store_dword v221, v96, s[0:1] offset:128
	s_add_u32 s0, s68, 0x41000
	s_addc_u32 s1, s69, 0
	global_store_dword v221, v113, s[0:1]
	global_store_dword v221, v97, s[0:1] offset:128
	s_add_u32 s0, s68, 0x42000
	s_addc_u32 s1, s69, 0
	global_store_dword v221, v114, s[0:1]
	global_store_dword v221, v98, s[0:1] offset:128
	s_add_u32 s0, s68, 0x43000
	s_addc_u32 s1, s69, 0
	global_store_dword v221, v115, s[0:1]
	global_store_dword v221, v99, s[0:1] offset:128
	s_add_u32 s0, s68, 0x48000
	s_addc_u32 s1, s69, 0
	global_store_dword v221, v116, s[0:1]
	global_store_dword v221, v100, s[0:1] offset:128
	s_add_u32 s0, s68, 0x49000
	s_addc_u32 s1, s69, 0
	global_store_dword v221, v117, s[0:1]
	global_store_dword v221, v101, s[0:1] offset:128
	s_add_u32 s0, s68, 0x4a000
	s_addc_u32 s1, s69, 0
	global_store_dword v221, v118, s[0:1]
	global_store_dword v221, v102, s[0:1] offset:128
	s_add_u32 s0, s68, 0x4b000
	s_addc_u32 s1, s69, 0
	global_store_dword v221, v119, s[0:1]
	global_store_dword v221, v103, s[0:1] offset:128
	s_add_u32 s0, s68, 0x50000
	s_addc_u32 s1, s69, 0
	global_store_dword v221, v120, s[0:1]
	global_store_dword v221, v104, s[0:1] offset:128
	s_add_u32 s0, s68, 0x51000
	s_addc_u32 s1, s69, 0
	global_store_dword v221, v121, s[0:1]
	global_store_dword v221, v105, s[0:1] offset:128
	s_add_u32 s0, s68, 0x52000
	s_addc_u32 s1, s69, 0
	global_store_dword v221, v122, s[0:1]
	global_store_dword v221, v106, s[0:1] offset:128
	s_add_u32 s0, s68, 0x53000
	s_addc_u32 s1, s69, 0
	global_store_dword v221, v123, s[0:1]
	global_store_dword v221, v107, s[0:1] offset:128
	s_add_u32 s0, s68, 0x58000
	s_addc_u32 s1, s69, 0
	global_store_dword v221, v124, s[0:1]
	global_store_dword v221, v108, s[0:1] offset:128
	s_add_u32 s0, s68, 0x59000
	s_addc_u32 s1, s69, 0
	global_store_dword v221, v125, s[0:1]
	global_store_dword v221, v109, s[0:1] offset:128
	s_add_u32 s0, s68, 0x5a000
	s_addc_u32 s1, s69, 0
	global_store_dword v221, v126, s[0:1]
	global_store_dword v221, v110, s[0:1] offset:128
	s_add_u32 s0, s68, 0x5b000
	s_addc_u32 s1, s69, 0
	global_store_dword v221, v127, s[0:1]
	global_store_dword v221, v111, s[0:1] offset:128
	s_add_u32 s0, s68, 0x60000
	s_addc_u32 s1, s69, 0
	global_store_dword v221, v80, s[0:1]
	global_store_dword v221, v64, s[0:1] offset:128
	s_add_u32 s0, s68, 0x61000
	s_addc_u32 s1, s69, 0
	global_store_dword v221, v81, s[0:1]
	global_store_dword v221, v65, s[0:1] offset:128
	s_add_u32 s0, s68, 0x62000
	s_addc_u32 s1, s69, 0
	global_store_dword v221, v82, s[0:1]
	global_store_dword v221, v66, s[0:1] offset:128
	s_add_u32 s0, s68, 0x63000
	s_addc_u32 s1, s69, 0
	global_store_dword v221, v83, s[0:1]
	global_store_dword v221, v67, s[0:1] offset:128
	s_add_u32 s0, s68, 0x68000
	s_addc_u32 s1, s69, 0
	global_store_dword v221, v84, s[0:1]
	global_store_dword v221, v68, s[0:1] offset:128
	s_add_u32 s0, s68, 0x69000
	s_addc_u32 s1, s69, 0
	global_store_dword v221, v85, s[0:1]
	global_store_dword v221, v69, s[0:1] offset:128
	s_add_u32 s0, s68, 0x6a000
	s_addc_u32 s1, s69, 0
	global_store_dword v221, v86, s[0:1]
	global_store_dword v221, v70, s[0:1] offset:128
	s_add_u32 s0, s68, 0x6b000
	s_addc_u32 s1, s69, 0
	global_store_dword v221, v87, s[0:1]
	global_store_dword v221, v71, s[0:1] offset:128
	s_add_u32 s0, s68, 0x70000
	s_addc_u32 s1, s69, 0
	global_store_dword v221, v88, s[0:1]
	global_store_dword v221, v72, s[0:1] offset:128
	s_add_u32 s0, s68, 0x71000
	s_addc_u32 s1, s69, 0
	global_store_dword v221, v89, s[0:1]
	global_store_dword v221, v73, s[0:1] offset:128
	s_add_u32 s0, s68, 0x72000
	s_addc_u32 s1, s69, 0
	global_store_dword v221, v90, s[0:1]
	global_store_dword v221, v74, s[0:1] offset:128
	s_add_u32 s0, s68, 0x73000
	s_addc_u32 s1, s69, 0
	global_store_dword v221, v91, s[0:1]
	global_store_dword v221, v75, s[0:1] offset:128
	s_add_u32 s0, s68, 0x78000
	s_addc_u32 s1, s69, 0
	global_store_dword v221, v92, s[0:1]
	global_store_dword v221, v76, s[0:1] offset:128
	s_add_u32 s0, s68, 0x79000
	s_addc_u32 s1, s69, 0
	global_store_dword v221, v93, s[0:1]
	global_store_dword v221, v77, s[0:1] offset:128
	s_add_u32 s0, s68, 0x7a000
	s_addc_u32 s1, s69, 0
	global_store_dword v221, v94, s[0:1]
	global_store_dword v221, v78, s[0:1] offset:128
	s_add_u32 s0, s68, 0x7b000
	s_addc_u32 s1, s69, 0
	global_store_dword v221, v95, s[0:1]
	global_store_dword v221, v79, s[0:1] offset:128
	s_branch .LBB0_267

.LBB0_1218:
	s_and_b64 vcc, exec, s[0:1]
	s_cbranch_vccz .LBB0_1561
	v_mov_b32_e32 v139, v224
	s_load_dword s6, s[24:25], 0x0
	v_readlane_b32 s0, v251, 34
	v_readlane_b32 s1, v251, 35
	v_and_b32_e32 v137, 63, v139
	s_andn2_b64 vcc, exec, s[0:1]
	s_cbranch_vccnz .LBB0_1673
	s_add_u32 s46, s66, 0x3f700
	s_addc_u32 s47, s67, 0
	v_lshrrev_b32_e32 v0, 3, v139
	v_and_b32_e32 v1, 7, v139
	v_lshlrev_b32_e32 v1, 3, v1
	v_lshl_or_b32 v0, v0, 7, v1
	global_load_dwordx2 v[246:247], v0, s[46:47]
	v_lshlrev_b32_e32 v245, 3, v139
	v_add_u32_e32 v245, 0x20000, v245
	v_readlane_b32 s0, v252, 55
	s_add_u32 s0, s66, s0
	s_addc_u32 s1, s67, 0
	v_readlane_b32 s4, v254, 52
	s_add_u32 s4, s0, s4
	v_readlane_b32 s0, v254, 48
	v_lshrrev_b32_e32 v0, 4, v139
	s_addc_u32 s5, s1, s0
	v_readlane_b32 s0, v252, 56
	v_xor_b32_e32 v0, v0, v139
	v_ashrrev_i32_e32 v5, 3, v139
	v_readlane_b32 s55, v252, 54
	s_add_u32 s44, s66, s0
	v_lshlrev_b32_e32 v0, 4, v0
	v_add_u32_e32 v2, s55, v5
	v_readlane_b32 s7, v252, 57
	s_addc_u32 s45, s67, 0
	v_and_b32_e32 v128, 0x70, v0
	v_mad_i64_i32 v[2:3], s[0:1], v2, s7, 0
	v_lshl_add_u32 v6, v139, 4, 0
	v_lshl_add_u64 v[0:1], s[44:45], 0, v[128:129]
	v_readfirstlane_b32 s0, v6
	v_add_u32_e32 v7, 0x200, v139
	v_lshl_add_u64 v[2:3], v[2:3], 1, v[0:1]
	s_mov_b32 m0, s0
	v_ashrrev_i32_e32 v8, 3, v7
	global_load_lds_dwordx4 v[2:3], off
	v_add_u32_e32 v2, s55, v8
	v_mad_i64_i32 v[2:3], s[0:1], v2, s7, 0
	v_lshl_add_u32 v7, v7, 4, 0
	v_add_u32_e32 v9, 0x400, v139
	v_readfirstlane_b32 s0, v7
	v_lshl_add_u64 v[2:3], v[2:3], 1, v[0:1]
	s_mov_b32 m0, s0
	v_ashrrev_i32_e32 v10, 3, v9
	global_load_lds_dwordx4 v[2:3], off
	v_add_u32_e32 v2, s55, v10
	v_mad_i64_i32 v[2:3], s[0:1], v2, s7, 0
	v_lshl_add_u32 v9, v9, 4, 0
	v_add_u32_e32 v11, 0x600, v139
	v_readfirstlane_b32 s0, v9
	v_lshl_add_u64 v[2:3], v[2:3], 1, v[0:1]
	s_mov_b32 m0, s0
	v_ashrrev_i32_e32 v12, 3, v11
	global_load_lds_dwordx4 v[2:3], off
	v_add_u32_e32 v2, s55, v12
	v_mad_i64_i32 v[2:3], s[0:1], v2, s7, 0
	v_lshl_add_u32 v11, v11, 4, 0
	v_readlane_b32 s54, v251, 36
	v_lshl_add_u64 v[0:1], v[2:3], 1, v[0:1]
	v_readfirstlane_b32 s0, v11
	v_add_u32_e32 v2, s54, v5
	s_mov_b32 m0, s0
	v_mad_i64_i32 v[2:3], s[0:1], s7, v2, 0
	v_add_u32_e32 v5, 0x8000, v6
	global_load_lds_dwordx4 v[0:1], off
	v_lshl_add_u64 v[0:1], s[4:5], 0, v[128:129]
	v_readfirstlane_b32 s0, v5
	v_lshl_add_u64 v[2:3], v[2:3], 1, v[0:1]
	s_mov_b32 m0, s0
	v_add_u32_e32 v5, 0x8000, v7
	global_load_lds_dwordx4 v[2:3], off
	v_add_u32_e32 v2, s54, v8
	v_mad_i64_i32 v[2:3], s[0:1], s7, v2, 0
	v_readfirstlane_b32 s0, v5
	v_lshl_add_u64 v[2:3], v[2:3], 1, v[0:1]
	s_mov_b32 m0, s0
	v_add_u32_e32 v5, 0x8000, v9
	global_load_lds_dwordx4 v[2:3], off
	v_add_u32_e32 v2, s54, v10
	v_mad_i64_i32 v[2:3], s[0:1], s7, v2, 0
	v_readfirstlane_b32 s0, v5
	v_lshl_add_u64 v[2:3], v[2:3], 1, v[0:1]
	s_mov_b32 m0, s0
	v_lshrrev_b32_e32 v4, 5, v137
	global_load_lds_dwordx4 v[2:3], off
	v_add_u32_e32 v2, s54, v12
	v_mad_i64_i32 v[2:3], s[0:1], s7, v2, 0
	v_lshl_add_u64 v[0:1], v[2:3], 1, v[0:1]
	v_add_u32_e32 v2, 0x8000, v11
	v_and_b32_e32 v141, 31, v139
	v_readfirstlane_b32 s0, v2
	s_mov_b32 m0, s0
	s_load_dword s0, s[24:25], 0x10
	global_load_lds_dwordx4 v[0:1], off
	v_ashrrev_i32_e32 v0, 1, v139
	v_and_b32_e32 v134, 0xffffff80, v0
	s_waitcnt lgkmcnt(0)
	s_lshr_b32 s0, s0, 16
	s_cmp_lg_u32 s0, 0
	s_cselect_b64 s[0:1], -1, 0
	s_cmp_lg_u64 s[0:1], 0
	s_addc_u32 s9, s6, 0
	s_add_u32 s96, s66, 0xdf53700
	s_addc_u32 s97, s67, 0
	v_readlane_b32 s0, v254, 49
	v_readlane_b32 s1, v254, 50
	s_add_u32 s0, s66, s0
	s_addc_u32 s1, s67, s1
	s_add_u32 s56, s0, 0x2c93700
	s_addc_u32 s57, s1, 0
	s_add_u32 s52, s66, 0xdad3700
	s_addc_u32 s53, s67, 0
	v_readlane_b32 s0, v254, 51
	s_add_u32 s0, s66, s0
	s_addc_u32 s1, s67, 0
	s_add_u32 s92, s0, 0x2c4b700
	s_addc_u32 s93, s1, 0
	s_add_u32 s30, s66, 0xc953700
	s_addc_u32 s31, s67, 0
	s_add_u32 s58, s66, 0xd3d3700
	v_and_b32_e32 v0, 8, v139
	s_addc_u32 s59, s67, 0
	v_lshlrev_b32_e32 v176, 2, v4
	v_cmp_eq_u32_e64 s[36:37], 0, v0
	v_and_b32_e32 v138, 0x5f, v139
	v_and_b32_e32 v0, 64, v139
	s_add_u32 s70, s66, 0xc053700
	v_readlane_b32 s0, v252, 58
	s_mov_b32 s12, 0x1ffff80
	s_mov_b32 s8, 0
	v_and_b32_e32 v143, 0xc0, v139
	v_lshlrev_b32_e32 v136, 3, v4
	v_and_b32_e32 v177, 7, v139
	v_cmp_lt_u32_e64 s[38:39], 15, v141
	v_or_b32_e32 v178, v176, v134
	v_ashrrev_i32_e32 v135, 31, v134
	v_cmp_ne_u32_e64 s[40:41], 0, v0
	v_subrev_u32_e32 v140, 64, v138
	v_subrev_u32_e32 v142, 32, v138
	v_or_b32_e32 v179, 32, v134
	v_or_b32_e32 v180, 64, v134
	v_or_b32_e32 v181, 0x60, v134
	s_addc_u32 s71, s67, 0
	v_readlane_b32 s13, v250, 0
	s_mov_b32 s60, s0
	s_mov_b32 s6, s7
	s_branch .LBB0_1224

.LBB0_1229:
	v_mov_b32_e32 v0, v224
	s_movk_i32 s0, 0xff
	v_and_b32_e32 v1, 31, v0
	v_lshrrev_b32_e32 v2, 1, v0
	v_and_or_b32 v1, v2, s12, v1
	v_lshlrev_b32_e32 v192, 7, v1
	v_lshlrev_b32_e32 v1, 7, v0
	v_and_b32_e32 v194, 0x6f80, v1
	v_lshrrev_b32_e32 v1, 5, v0
	v_bfe_u32 v3, v0, 1, 3
	v_bfe_u32 v2, v0, 5, 1
	v_bitop3_b32 v1, v1, v3, 1 bitop3:0x6c
	v_lshlrev_b32_e32 v195, 4, v1
	v_bitop3_b32 v1, v2, v3, 2 bitop3:0x36
	v_lshlrev_b32_e32 v193, 4, v1
	v_bitop3_b32 v1, v2, v3, 4 bitop3:0x36
	v_lshrrev_b32_e32 v4, 4, v0
	v_ashrrev_i32_e32 v199, 3, v0
	v_lshlrev_b32_e32 v183, 4, v1
	v_bitop3_b32 v1, v2, v3, 6 bitop3:0x36
	v_cmp_gt_i32_e32 vcc, s73, v0
	v_cmp_lt_i32_e64 s[0:1], s0, v0
	v_xor_b32_e32 v200, v4, v0
	v_lshlrev_b32_e32 v191, 4, v0
	v_add_u32_e32 v5, 0x200, v0
	v_add_u32_e32 v6, 0x400, v0
	v_add_u32_e32 v7, 0x600, v0
	v_lshrrev_b32_e32 v187, 3, v0
	v_lshlrev_b32_e32 v182, 4, v1
	v_add_u32_e32 v1, s55, v199
	v_bitop3_b32 v0, v4, 7, v0 bitop3:0x48
	v_ashrrev_i32_e32 v2, 31, v1
	s_lshl_b64 s[18:19], s[60:61], 7
	v_lshlrev_b32_e32 v128, 4, v0
	v_lshlrev_b32_e32 v0, 1, v1
	s_add_u32 s17, s18, 0xffffff80
	v_alignbit_b32 v3, v2, v1, 31
	v_mad_u64_u32 v[0:1], s[18:19], v0, s6, v[128:129]
	v_mov_b32_e32 v2, v1
	v_ashrrev_i32_e32 v198, 3, v5
	s_add_u32 s44, s44, 0x80
	v_mad_u64_u32 v[2:3], s[18:19], v3, s6, v[2:3]
	v_lshlrev_b32_e32 v190, 4, v5
	v_lshrrev_b32_e32 v186, 3, v5
	v_add_u32_e32 v5, s55, v198
	s_addc_u32 s45, s45, 0
	v_mov_b32_e32 v1, v2
	v_lshl_add_u64 v[144:145], s[44:45], 0, v[0:1]
	v_lshlrev_b32_e32 v0, 1, v5
	v_ashrrev_i32_e32 v197, 3, v6
	v_lshlrev_b32_e32 v189, 4, v6
	v_lshrrev_b32_e32 v185, 3, v6
	v_ashrrev_i32_e32 v6, 31, v5
	v_mad_u64_u32 v[0:1], s[18:19], v0, s6, v[128:129]
	v_alignbit_b32 v3, v6, v5, 31
	v_mov_b32_e32 v2, v1
	v_mad_u64_u32 v[2:3], s[18:19], v3, s6, v[2:3]
	v_ashrrev_i32_e32 v196, 3, v7
	v_lshlrev_b32_e32 v188, 4, v7
	v_lshrrev_b32_e32 v184, 3, v7
	v_add_u32_e32 v7, s55, v197
	v_mov_b32_e32 v1, v2
	v_lshl_add_u64 v[146:147], s[44:45], 0, v[0:1]
	v_lshlrev_b32_e32 v0, 1, v7
	v_ashrrev_i32_e32 v8, 31, v7
	v_mad_u64_u32 v[0:1], s[18:19], v0, s6, v[128:129]
	v_alignbit_b32 v3, v8, v7, 31
	v_mov_b32_e32 v2, v1
	v_mad_u64_u32 v[2:3], s[18:19], v3, s6, v[2:3]
	v_add_u32_e32 v9, s55, v196
	v_mov_b32_e32 v1, v2
	v_lshl_add_u64 v[148:149], s[44:45], 0, v[0:1]
	v_lshlrev_b32_e32 v0, 1, v9
	v_ashrrev_i32_e32 v10, 31, v9
	v_mad_u64_u32 v[0:1], s[18:19], v0, s6, v[128:129]
	v_alignbit_b32 v3, v10, v9, 31
	v_mov_b32_e32 v2, v1
	v_mad_u64_u32 v[2:3], s[18:19], v3, s6, v[2:3]
	v_add_u32_e32 v19, s54, v199
	v_mov_b32_e32 v1, v2
	v_lshl_add_u64 v[150:151], s[44:45], 0, v[0:1]
	v_lshlrev_b32_e32 v0, 1, v19
	v_ashrrev_i32_e32 v20, 31, v19
	v_mad_u64_u32 v[0:1], s[18:19], v0, s6, v[128:129]
	v_alignbit_b32 v3, v20, v19, 31
	v_mov_b32_e32 v2, v1
	s_add_u32 s4, s4, 0x80
	v_mad_u64_u32 v[2:3], s[18:19], v3, s6, v[2:3]
	v_add_u32_e32 v21, s54, v198
	s_addc_u32 s5, s5, 0
	v_mov_b32_e32 v1, v2
	v_lshl_add_u64 v[152:153], s[4:5], 0, v[0:1]
	v_lshlrev_b32_e32 v0, 1, v21
	v_ashrrev_i32_e32 v22, 31, v21
	v_mad_u64_u32 v[0:1], s[18:19], v0, s6, v[128:129]
	v_alignbit_b32 v3, v22, v21, 31
	v_mov_b32_e32 v2, v1
	v_mad_u64_u32 v[2:3], s[18:19], v3, s6, v[2:3]
	v_add_u32_e32 v23, s54, v197
	v_mov_b32_e32 v1, v2
	v_lshl_add_u64 v[154:155], s[4:5], 0, v[0:1]
	v_lshlrev_b32_e32 v0, 1, v23
	v_ashrrev_i32_e32 v24, 31, v23
	v_mad_u64_u32 v[0:1], s[18:19], v0, s6, v[128:129]
	v_alignbit_b32 v3, v24, v23, 31
	v_mov_b32_e32 v2, v1
	v_mad_u64_u32 v[2:3], s[18:19], v3, s6, v[2:3]
	v_add_u32_e32 v25, s54, v196
	v_mov_b32_e32 v1, v2
	v_lshl_add_u64 v[156:157], s[4:5], 0, v[0:1]
	v_lshlrev_b32_e32 v0, 1, v25
	v_ashrrev_i32_e32 v26, 31, v25
	v_mad_u64_u32 v[0:1], s[18:19], v0, s6, v[128:129]
	v_alignbit_b32 v3, v26, v25, 31
	v_mov_b32_e32 v2, v1
	v_mad_u64_u32 v[2:3], s[18:19], v3, s6, v[2:3]
	v_add_u32_e32 v11, s55, v187
	v_mov_b32_e32 v1, v2
	v_lshl_add_u64 v[158:159], s[4:5], 0, v[0:1]
	v_lshlrev_b32_e32 v0, 1, v11
	v_ashrrev_i32_e32 v12, 31, v11
	v_mad_u64_u32 v[0:1], s[18:19], v0, s6, v[128:129]
	v_alignbit_b32 v3, v12, v11, 31
	v_mov_b32_e32 v2, v1
	v_mad_u64_u32 v[2:3], s[18:19], v3, s6, v[2:3]
	v_add_u32_e32 v13, s55, v186
	v_mov_b32_e32 v1, v2
	v_lshl_add_u64 v[160:161], s[44:45], 0, v[0:1]
	v_lshlrev_b32_e32 v0, 1, v13
	v_ashrrev_i32_e32 v14, 31, v13
	v_mad_u64_u32 v[0:1], s[18:19], v0, s6, v[128:129]
	v_alignbit_b32 v3, v14, v13, 31
	v_mov_b32_e32 v2, v1
	v_mad_u64_u32 v[2:3], s[18:19], v3, s6, v[2:3]
	v_add_u32_e32 v15, s55, v185
	v_mov_b32_e32 v1, v2
	v_lshl_add_u64 v[162:163], s[44:45], 0, v[0:1]
	v_lshlrev_b32_e32 v0, 1, v15
	v_ashrrev_i32_e32 v16, 31, v15
	v_mad_u64_u32 v[0:1], s[18:19], v0, s6, v[128:129]
	v_alignbit_b32 v3, v16, v15, 31
	v_mov_b32_e32 v2, v1
	v_mad_u64_u32 v[2:3], s[18:19], v3, s6, v[2:3]
	v_add_u32_e32 v17, s55, v184
	v_mov_b32_e32 v1, v2
	v_lshl_add_u64 v[164:165], s[44:45], 0, v[0:1]
	v_lshlrev_b32_e32 v0, 1, v17
	v_ashrrev_i32_e32 v18, 31, v17
	v_mad_u64_u32 v[0:1], s[18:19], v0, s6, v[128:129]
	v_alignbit_b32 v3, v18, v17, 31
	v_mov_b32_e32 v2, v1
	v_mad_u64_u32 v[2:3], s[18:19], v3, s6, v[2:3]
	v_mov_b32_e32 v1, v2
	v_add_u32_e32 v27, s54, v187
	v_lshl_add_u64 v[166:167], s[44:45], 0, v[0:1]
	s_lshl_b32 s44, s6, 1
	v_mad_u64_u32 v[0:1], s[18:19], s44, v27, v[128:129]
	v_mov_b32_e32 v2, v1
	s_lshr_b32 s18, s6, 31
	v_mad_u64_u32 v[2:3], s[6:7], s18, v27, v[2:3]
	v_add_u32_e32 v28, s54, v186
	v_mov_b32_e32 v1, v2
	v_lshl_add_u64 v[168:169], s[4:5], 0, v[0:1]
	v_mad_u64_u32 v[0:1], s[6:7], s44, v28, v[128:129]
	v_mov_b32_e32 v2, v1
	v_mad_u64_u32 v[2:3], s[6:7], s18, v28, v[2:3]
	v_add_u32_e32 v29, s54, v185
	v_mov_b32_e32 v1, v2
	v_lshl_add_u64 v[170:171], s[4:5], 0, v[0:1]
	v_mad_u64_u32 v[0:1], s[6:7], s44, v29, v[128:129]
	v_mov_b32_e32 v2, v1
	v_mad_u64_u32 v[2:3], s[6:7], s18, v29, v[2:3]
	v_add_u32_e32 v30, s54, v184
	v_mov_b32_e32 v1, v2
	v_lshl_add_u64 v[172:173], s[4:5], 0, v[0:1]
	v_mad_u64_u32 v[0:1], s[6:7], s44, v30, v[128:129]
	v_mov_b32_e32 v2, v1
	v_mad_u64_u32 v[2:3], s[6:7], s18, v30, v[2:3]
	s_waitcnt vmcnt(0)
	v_mov_b32_e32 v1, v2
	v_lshl_add_u64 v[174:175], s[4:5], 0, v[0:1]
	v_mov_b32_e32 v0, 0
	s_mov_b64 s[4:5], 0
	v_mov_b32_e32 v1, v0
	v_mov_b32_e32 v2, v0
	v_mov_b32_e32 v3, v0
	v_mov_b32_e32 v4, v0
	v_mov_b32_e32 v5, v0
	v_mov_b32_e32 v6, v0
	v_mov_b32_e32 v7, v0
	v_mov_b32_e32 v8, v0
	v_mov_b32_e32 v9, v0
	v_mov_b32_e32 v10, v0
	v_mov_b32_e32 v11, v0
	v_mov_b32_e32 v12, v0
	v_mov_b32_e32 v13, v0
	v_mov_b32_e32 v14, v0
	v_mov_b32_e32 v15, v0
	v_mov_b32_e32 v16, v0
	v_mov_b32_e32 v17, v0
	v_mov_b32_e32 v18, v0
	v_mov_b32_e32 v19, v0
	v_mov_b32_e32 v20, v0
	v_mov_b32_e32 v21, v0
	v_mov_b32_e32 v22, v0
	v_mov_b32_e32 v23, v0
	v_mov_b32_e32 v24, v0
	v_mov_b32_e32 v25, v0
	v_mov_b32_e32 v26, v0
	v_mov_b32_e32 v27, v0
	v_mov_b32_e32 v28, v0
	v_mov_b32_e32 v29, v0
	v_mov_b32_e32 v30, v0
	v_mov_b32_e32 v31, v0
	v_mov_b32_e32 v32, v0
	v_mov_b32_e32 v33, v0
	v_mov_b32_e32 v34, v0
	v_mov_b32_e32 v35, v0
	v_mov_b32_e32 v36, v0
	v_mov_b32_e32 v37, v0
	v_mov_b32_e32 v38, v0
	v_mov_b32_e32 v39, v0
	v_mov_b32_e32 v40, v0
	v_mov_b32_e32 v41, v0
	v_mov_b32_e32 v42, v0
	v_mov_b32_e32 v43, v0
	v_mov_b32_e32 v44, v0
	v_mov_b32_e32 v45, v0
	v_mov_b32_e32 v46, v0
	v_mov_b32_e32 v47, v0
	v_mov_b32_e32 v48, v0
	v_mov_b32_e32 v49, v0
	v_mov_b32_e32 v50, v0
	v_mov_b32_e32 v51, v0
	v_mov_b32_e32 v52, v0
	v_mov_b32_e32 v53, v0
	v_mov_b32_e32 v54, v0
	v_mov_b32_e32 v55, v0
	v_mov_b32_e32 v56, v0
	v_mov_b32_e32 v57, v0
	v_mov_b32_e32 v58, v0
	v_mov_b32_e32 v59, v0
	v_mov_b32_e32 v60, v0
	v_mov_b32_e32 v61, v0
	v_mov_b32_e32 v62, v0
	v_mov_b32_e32 v63, v0
	v_mov_b32_e32 v64, v0
	v_mov_b32_e32 v65, v0
	v_mov_b32_e32 v66, v0
	v_mov_b32_e32 v67, v0
	v_mov_b32_e32 v68, v0
	v_mov_b32_e32 v69, v0
	v_mov_b32_e32 v70, v0
	v_mov_b32_e32 v71, v0
	v_mov_b32_e32 v72, v0
	v_mov_b32_e32 v73, v0
	v_mov_b32_e32 v74, v0
	v_mov_b32_e32 v75, v0
	v_mov_b32_e32 v76, v0
	v_mov_b32_e32 v77, v0
	v_mov_b32_e32 v78, v0
	v_mov_b32_e32 v79, v0
	v_mov_b32_e32 v80, v0
	v_mov_b32_e32 v81, v0
	v_mov_b32_e32 v82, v0
	v_mov_b32_e32 v83, v0
	v_mov_b32_e32 v84, v0
	v_mov_b32_e32 v85, v0
	v_mov_b32_e32 v86, v0
	v_mov_b32_e32 v87, v0
	v_mov_b32_e32 v88, v0
	v_mov_b32_e32 v89, v0
	v_mov_b32_e32 v90, v0
	v_mov_b32_e32 v91, v0
	v_mov_b32_e32 v92, v0
	v_mov_b32_e32 v93, v0
	v_mov_b32_e32 v94, v0
	v_mov_b32_e32 v95, v0
	v_mov_b32_e32 v96, v0
	v_mov_b32_e32 v97, v0
	v_mov_b32_e32 v98, v0
	v_mov_b32_e32 v99, v0
	v_mov_b32_e32 v100, v0
	v_mov_b32_e32 v101, v0
	v_mov_b32_e32 v102, v0
	v_mov_b32_e32 v103, v0
	v_mov_b32_e32 v104, v0
	v_mov_b32_e32 v105, v0
	v_mov_b32_e32 v106, v0
	v_mov_b32_e32 v107, v0
	v_mov_b32_e32 v108, v0
	v_mov_b32_e32 v109, v0
	v_mov_b32_e32 v110, v0
	v_mov_b32_e32 v111, v0
	v_mov_b32_e32 v112, v0
	v_mov_b32_e32 v113, v0
	v_mov_b32_e32 v114, v0
	v_mov_b32_e32 v115, v0
	v_mov_b32_e32 v116, v0
	v_mov_b32_e32 v117, v0
	v_mov_b32_e32 v118, v0
	v_mov_b32_e32 v119, v0
	v_mov_b32_e32 v120, v0
	v_mov_b32_e32 v121, v0
	v_mov_b32_e32 v122, v0
	v_mov_b32_e32 v123, v0
	v_mov_b32_e32 v124, v0
	v_mov_b32_e32 v125, v0
	v_mov_b32_e32 v126, v0
	v_mov_b32_e32 v127, v0
	s_waitcnt vmcnt(0)
	ds_write_b64 v245, v[246:247]
	s_waitcnt lgkmcnt(0)
	s_barrier
	s_lshl_b32 s44, s8, 16
	s_and_saveexec_b64 s[6:7], vcc
	s_cbranch_execz .LBB0_1232
	s_branch .LBB0_1231
